# G2m epilogue: cross-row sums of the LayerNorm partials by v_permlane16_swap / v_permlane32_swap instead of ds_bpermute round trips (16 per unit)
# speedup vs baseline: 1.0114x; 1.0012x over previous
.LBB0_743:
	v_and_b32_e32 v1, 64, v211
	s_lshl_b32 s0, s40, 7
	v_xor_b32_e32 v0, 16, v211
	v_add_u32_e32 v1, 64, v1
	s_or_b32 s0, s0, s61
	s_lshl_b32 s26, s2, 8
	v_cmp_lt_i32_e32 vcc, v0, v1
	v_lshl_add_u32 v146, v130, 3, s0
	s_add_i32 s0, s26, s77
	v_cndmask_b32_e32 v0, v211, v0, vcc
	v_add_u32_e32 v150, s0, v214
	v_lshlrev_b32_e32 v216, 2, v0
	v_xor_b32_e32 v0, 32, v211
	v_cmp_lt_i32_e32 vcc, v0, v1
	v_ashrrev_i32_e32 v151, 31, v150
	v_lshlrev_b64 v[154:155], 11, v[150:151]
	v_cndmask_b32_e32 v0, v211, v0, vcc
	v_ashrrev_i32_e32 v147, 31, v146
	v_lshlrev_b32_e32 v215, 2, v0
	v_lshl_add_u64 v[0:1], s[16:17], 0, v[154:155]
	v_lshl_add_u64 v[0:1], v[146:147], 1, v[0:1]
	v_cmp_eq_u32_e32 vcc, 0, v130
	global_load_dwordx4 v[220:223], v[0:1], off
	v_add_u32_e32 v224, 16, v150
	v_ashrrev_i32_e32 v225, 31, v224
	v_lshlrev_b64 v[224:225], 11, v[224:225]
	v_lshl_add_u64 v[224:225], s[16:17], 0, v[224:225]
	v_lshl_add_u64 v[224:225], v[146:147], 1, v[224:225]
	global_load_dwordx4 v[224:227], v[224:225], off
	v_add_u32_e32 v228, 32, v150
	v_ashrrev_i32_e32 v229, 31, v228
	v_lshlrev_b64 v[228:229], 11, v[228:229]
	v_lshl_add_u64 v[228:229], s[16:17], 0, v[228:229]
	v_lshl_add_u64 v[228:229], v[146:147], 1, v[228:229]
	global_load_dwordx4 v[228:231], v[228:229], off
	v_add_u32_e32 v232, 48, v150
	v_ashrrev_i32_e32 v233, 31, v232
	v_lshlrev_b64 v[232:233], 11, v[232:233]
	v_lshl_add_u64 v[232:233], s[16:17], 0, v[232:233]
	v_lshl_add_u64 v[232:233], v[146:147], 1, v[232:233]
	global_load_dwordx4 v[232:235], v[232:233], off
	v_add_u32_e32 v236, 128, v150
	v_ashrrev_i32_e32 v237, 31, v236
	v_lshlrev_b64 v[236:237], 11, v[236:237]
	v_lshl_add_u64 v[236:237], s[16:17], 0, v[236:237]
	v_lshl_add_u64 v[236:237], v[146:147], 1, v[236:237]
	global_load_dwordx4 v[236:239], v[236:237], off
	v_add_u32_e32 v242, 144, v150
	v_ashrrev_i32_e32 v243, 31, v242
	v_lshlrev_b64 v[242:243], 11, v[242:243]
	v_lshl_add_u64 v[242:243], s[16:17], 0, v[242:243]
	v_lshl_add_u64 v[242:243], v[146:147], 1, v[242:243]
	global_load_dwordx4 v[242:245], v[242:243], off
	v_add_u32_e32 v246, 160, v150
	v_ashrrev_i32_e32 v247, 31, v246
	v_lshlrev_b64 v[246:247], 11, v[246:247]
	v_lshl_add_u64 v[246:247], s[16:17], 0, v[246:247]
	v_lshl_add_u64 v[246:247], v[146:147], 1, v[246:247]
	global_load_dwordx4 v[246:249], v[246:247], off
	v_add_u32_e32 v250, 176, v150
	v_ashrrev_i32_e32 v251, 31, v250
	v_lshlrev_b64 v[250:251], 11, v[250:251]
	v_lshl_add_u64 v[250:251], s[16:17], 0, v[250:251]
	v_lshl_add_u64 v[250:251], v[146:147], 1, v[250:251]
	global_load_dwordx4 v[250:253], v[250:251], off
	v_mul_f32_e32 v0, 0xbfb8aa3b, v126
	v_mul_f32_e32 v1, 0xbfb8aa3b, v127
	v_exp_f32_e32 v0, v0
	v_exp_f32_e32 v1, v1
	v_mul_f32_e32 v122, 0xbfb8aa3b, v122
	v_mul_f32_e32 v123, 0xbfb8aa3b, v123
	v_add_f32_e32 v0, 1.0, v0
	v_add_f32_e32 v1, 1.0, v1
	v_rcp_f32_e32 v0, v0
	v_rcp_f32_e32 v1, v1
	v_exp_f32_e32 v122, v122
	v_exp_f32_e32 v123, v123
	v_add_u32_e32 v152, s96, v214
	v_add_f32_e32 v122, 1.0, v122
	v_add_f32_e32 v123, 1.0, v123
	v_rcp_f32_e32 v122, v122
	v_rcp_f32_e32 v123, v123
	s_waitcnt vmcnt(7)
	v_lshlrev_b32_e32 v126, 16, v220
	v_and_b32_e32 v127, 0xffff0000, v220
	v_pk_mul_f32 v[126:127], v[0:1], v[126:127]
	v_mul_f32_e32 v1, 0xbfb8aa3b, v129
	v_add_f32_e32 v0, 0, v126
	v_add_f32_e32 v130, v127, v0
	v_mul_f32_e32 v0, 0xbfb8aa3b, v128
	v_exp_f32_e32 v0, v0
	v_exp_f32_e32 v1, v1
	v_lshlrev_b32_e32 v128, 16, v221
	v_and_b32_e32 v129, 0xffff0000, v221
	v_add_f32_e32 v0, 1.0, v0
	v_add_f32_e32 v1, 1.0, v1
	v_rcp_f32_e32 v0, v0
	v_rcp_f32_e32 v1, v1
	s_nop 0
	v_pk_mul_f32 v[128:129], v[0:1], v[128:129]
	s_nop 0
	v_add_f32_e32 v131, v128, v130
	v_mul_f32_e32 v130, v126, v126
	v_mov_b32_e32 v0, v128
	v_mov_b32_e32 v1, v126
	v_fmac_f32_e32 v130, v127, v127
	v_pk_fma_f32 v[0:1], v[0:1], v[0:1], v[130:131] op_sel_hi:[1,1,0]
	v_add_f32_e32 v148, v129, v131
	v_lshlrev_b32_e32 v130, 16, v222
	v_and_b32_e32 v131, 0xffff0000, v222
	v_pk_mul_f32 v[130:131], v[122:123], v[130:131]
	v_mul_f32_e32 v132, v129, v129
	v_mov_b32_e32 v122, v130
	v_mov_b32_e32 v123, v129
	v_pk_add_f32 v[0:1], v[132:133], v[0:1] op_sel_hi:[0,1]
	v_pk_fma_f32 v[122:123], v[122:123], v[122:123], v[0:1]
	v_mul_f32_e32 v0, 0xbfb8aa3b, v124
	v_mul_f32_e32 v1, 0xbfb8aa3b, v125
	v_exp_f32_e32 v0, v0
	v_exp_f32_e32 v1, v1
	v_add_f32_e32 v148, v130, v148
	v_lshlrev_b32_e32 v124, 16, v223
	v_add_f32_e32 v0, 1.0, v0
	v_add_f32_e32 v1, 1.0, v1
	v_rcp_f32_e32 v0, v0
	v_rcp_f32_e32 v1, v1
	v_and_b32_e32 v125, 0xffff0000, v223
	v_add_f32_e32 v132, v131, v148
	v_pk_mul_f32 v[156:157], v[0:1], v[124:125]
	s_nop 0
	v_add_f32_e32 v0, v156, v132
	v_mul_f32_e32 v132, v131, v131
	v_mov_b32_e32 v124, v156
	v_mov_b32_e32 v125, v131
	v_pk_add_f32 v[122:123], v[132:133], v[122:123] op_sel_hi:[0,1]
	v_pk_fma_f32 v[122:123], v[124:125], v[124:125], v[122:123]
	v_pk_mul_f32 v[124:125], v[156:157], v[156:157]
	v_pk_mov_b32 v[122:123], v[156:157], v[122:123] op_sel:[1,0]
	v_mov_b32_e32 v1, v125
	v_pk_add_f32 v[0:1], v[122:123], v[0:1]
	v_mov_b32_e32 v122, v0
	v_mov_b32_e32 v123, v1
	s_nop 1
	v_permlane16_swap_b32_e32 v122, v0
	v_permlane16_swap_b32_e32 v123, v1
	s_waitcnt lgkmcnt(0)
	v_pk_add_f32 v[122:123], v[0:1], v[122:123]
	v_mov_b32_e32 v124, v122
	v_mov_b32_e32 v125, v123
	s_nop 1
	v_permlane32_swap_b32_e32 v124, v122
	v_permlane32_swap_b32_e32 v125, v123
	s_and_saveexec_b64 s[0:1], vcc
	s_cbranch_execz .LBB0_745
	v_lshl_add_u32 v0, v152, 3, 0
	v_add_u32_e32 v132, 0x20000, v0
	s_waitcnt lgkmcnt(0)
	v_pk_add_f32 v[0:1], v[122:123], v[124:125]
	ds_write_b64 v132, v[0:1]
.LBB0_745:
	s_or_b64 exec, exec, s[0:1]
	v_add_u32_e32 v0, 16, v150
	v_ashrrev_i32_e32 v1, 31, v0
	v_lshlrev_b64 v[192:193], 11, v[0:1]
	v_lshl_add_u64 v[0:1], s[16:17], 0, v[192:193]
	v_lshl_add_u64 v[0:1], v[146:147], 1, v[0:1]
	s_waitcnt lgkmcnt(0)
	s_nop 0
	v_mul_f32_e32 v0, 0xbfb8aa3b, v118
	v_mul_f32_e32 v1, 0xbfb8aa3b, v119
	v_exp_f32_e32 v0, v0
	v_exp_f32_e32 v1, v1
	v_mul_f32_e32 v114, 0xbfb8aa3b, v114
	v_mul_f32_e32 v115, 0xbfb8aa3b, v115
	v_add_f32_e32 v0, 1.0, v0
	v_add_f32_e32 v1, 1.0, v1
	v_rcp_f32_e32 v0, v0
	v_rcp_f32_e32 v1, v1
	v_exp_f32_e32 v114, v114
	v_exp_f32_e32 v115, v115
	v_lshl_add_u32 v217, v152, 3, s71
	v_add_f32_e32 v114, 1.0, v114
	v_add_f32_e32 v115, 1.0, v115
	v_rcp_f32_e32 v114, v114
	v_rcp_f32_e32 v115, v115
	s_waitcnt vmcnt(6)
	v_lshlrev_b32_e32 v118, 16, v224
	v_and_b32_e32 v119, 0xffff0000, v224
	v_pk_mul_f32 v[132:133], v[0:1], v[118:119]
	v_mul_f32_e32 v1, 0xbfb8aa3b, v121
	v_add_f32_e32 v0, 0, v132
	v_add_f32_e32 v122, v133, v0
	v_mul_f32_e32 v0, 0xbfb8aa3b, v120
	v_exp_f32_e32 v0, v0
	v_exp_f32_e32 v1, v1
	v_lshlrev_b32_e32 v118, 16, v225
	v_and_b32_e32 v119, 0xffff0000, v225
	v_add_f32_e32 v0, 1.0, v0
	v_add_f32_e32 v1, 1.0, v1
	v_rcp_f32_e32 v0, v0
	v_rcp_f32_e32 v1, v1
	s_nop 0
	v_pk_mul_f32 v[148:149], v[0:1], v[118:119]
	v_mul_f32_e32 v118, v132, v132
	v_add_f32_e32 v119, v148, v122
	v_mov_b32_e32 v0, v148
	v_mov_b32_e32 v1, v132
	v_fmac_f32_e32 v118, v133, v133
	v_pk_fma_f32 v[0:1], v[0:1], v[0:1], v[118:119] op_sel_hi:[1,1,0]
	v_add_f32_e32 v120, v149, v119
	v_lshlrev_b32_e32 v118, 16, v226
	v_and_b32_e32 v119, 0xffff0000, v226
	v_pk_mul_f32 v[158:159], v[114:115], v[118:119]
	v_mul_f32_e32 v118, v149, v149
	v_add_f32_e32 v119, v158, v120
	v_mov_b32_e32 v114, v158
	v_mov_b32_e32 v115, v149
	v_pk_add_f32 v[0:1], v[118:119], v[0:1] op_sel_hi:[0,1]
	v_pk_fma_f32 v[0:1], v[114:115], v[114:115], v[0:1]
	v_mul_f32_e32 v114, 0xbfb8aa3b, v116
	v_mul_f32_e32 v115, 0xbfb8aa3b, v117
	v_exp_f32_e32 v114, v114
	v_exp_f32_e32 v115, v115
	v_lshlrev_b32_e32 v116, 16, v227
	v_and_b32_e32 v117, 0xffff0000, v227
	v_add_f32_e32 v114, 1.0, v114
	v_add_f32_e32 v115, 1.0, v115
	v_rcp_f32_e32 v114, v114
	v_rcp_f32_e32 v115, v115
	v_add_f32_e32 v118, v159, v119
	v_pk_mul_f32 v[174:175], v[114:115], v[116:117]
	s_nop 0
	v_add_f32_e32 v114, v174, v118
	v_mul_f32_e32 v118, v159, v159
	v_mov_b32_e32 v116, v174
	v_mov_b32_e32 v117, v159
	v_pk_add_f32 v[0:1], v[118:119], v[0:1] op_sel_hi:[0,1]
	v_pk_fma_f32 v[0:1], v[116:117], v[116:117], v[0:1]
	v_pk_mul_f32 v[116:117], v[174:175], v[174:175]
	v_pk_mov_b32 v[0:1], v[174:175], v[0:1] op_sel:[1,0]
	v_mov_b32_e32 v115, v117
	v_pk_add_f32 v[0:1], v[0:1], v[114:115]
	v_mov_b32_e32 v114, v0
	v_mov_b32_e32 v115, v1
	s_nop 1
	v_permlane16_swap_b32_e32 v114, v0
	v_permlane16_swap_b32_e32 v115, v1
	s_waitcnt lgkmcnt(0)
	v_pk_add_f32 v[114:115], v[0:1], v[114:115]
	v_mov_b32_e32 v116, v114
	v_mov_b32_e32 v117, v115
	s_nop 1
	v_permlane32_swap_b32_e32 v116, v114
	v_permlane32_swap_b32_e32 v117, v115
	s_and_saveexec_b64 s[0:1], vcc
	v_readlane_b32 s84, v255, 39
	v_readlane_b32 s85, v255, 40
	s_cbranch_execz .LBB0_747
	s_waitcnt lgkmcnt(0)
	v_pk_add_f32 v[0:1], v[114:115], v[116:117]
	ds_write_b64 v217, v[0:1] offset:128
.LBB0_747:
	s_or_b64 exec, exec, s[0:1]
	v_add_u32_e32 v0, 32, v150
	v_ashrrev_i32_e32 v1, 31, v0
	v_lshlrev_b64 v[196:197], 11, v[0:1]
	v_lshl_add_u64 v[0:1], s[16:17], 0, v[196:197]
	v_lshl_add_u64 v[0:1], v[146:147], 1, v[0:1]
	s_waitcnt lgkmcnt(0)
	s_nop 0
	v_mul_f32_e32 v0, 0xbfb8aa3b, v110
	v_mul_f32_e32 v1, 0xbfb8aa3b, v111
	v_exp_f32_e32 v0, v0
	v_exp_f32_e32 v1, v1
	v_mul_f32_e32 v106, 0xbfb8aa3b, v106
	v_mul_f32_e32 v107, 0xbfb8aa3b, v107
	v_add_f32_e32 v0, 1.0, v0
	v_add_f32_e32 v1, 1.0, v1
	v_rcp_f32_e32 v0, v0
	v_rcp_f32_e32 v1, v1
	v_exp_f32_e32 v106, v106
	v_exp_f32_e32 v107, v107
	v_add_f32_e32 v106, 1.0, v106
	v_add_f32_e32 v107, 1.0, v107
	v_rcp_f32_e32 v106, v106
	v_rcp_f32_e32 v107, v107
	s_waitcnt vmcnt(5)
	v_lshlrev_b32_e32 v110, 16, v228
	v_and_b32_e32 v111, 0xffff0000, v228
	v_pk_mul_f32 v[162:163], v[0:1], v[110:111]
	v_mul_f32_e32 v1, 0xbfb8aa3b, v113
	v_add_f32_e32 v0, 0, v162
	v_add_f32_e32 v114, v163, v0
	v_mul_f32_e32 v0, 0xbfb8aa3b, v112
	v_exp_f32_e32 v0, v0
	v_exp_f32_e32 v1, v1
	v_lshlrev_b32_e32 v110, 16, v229
	v_and_b32_e32 v111, 0xffff0000, v229
	v_add_f32_e32 v0, 1.0, v0
	v_add_f32_e32 v1, 1.0, v1
	v_rcp_f32_e32 v0, v0
	v_rcp_f32_e32 v1, v1
	s_nop 0
	v_pk_mul_f32 v[166:167], v[0:1], v[110:111]
	v_mul_f32_e32 v110, v162, v162
	v_add_f32_e32 v111, v166, v114
	v_mov_b32_e32 v0, v166
	v_mov_b32_e32 v1, v162
	v_fmac_f32_e32 v110, v163, v163
	v_pk_fma_f32 v[0:1], v[0:1], v[0:1], v[110:111] op_sel_hi:[1,1,0]
	v_add_f32_e32 v112, v167, v111
	v_lshlrev_b32_e32 v110, 16, v230
	v_and_b32_e32 v111, 0xffff0000, v230
	v_pk_mul_f32 v[172:173], v[106:107], v[110:111]
	v_mul_f32_e32 v110, v167, v167
	v_add_f32_e32 v111, v172, v112
	v_mov_b32_e32 v106, v172
	v_mov_b32_e32 v107, v167
	v_pk_add_f32 v[0:1], v[110:111], v[0:1] op_sel_hi:[0,1]
	v_pk_fma_f32 v[0:1], v[106:107], v[106:107], v[0:1]
	v_mul_f32_e32 v106, 0xbfb8aa3b, v108
	v_mul_f32_e32 v107, 0xbfb8aa3b, v109
	v_exp_f32_e32 v106, v106
	v_exp_f32_e32 v107, v107
	v_lshlrev_b32_e32 v108, 16, v231
	v_and_b32_e32 v109, 0xffff0000, v231
	v_add_f32_e32 v106, 1.0, v106
	v_add_f32_e32 v107, 1.0, v107
	v_rcp_f32_e32 v106, v106
	v_rcp_f32_e32 v107, v107
	v_add_f32_e32 v110, v173, v111
	v_pk_mul_f32 v[184:185], v[106:107], v[108:109]
	s_nop 0
	v_add_f32_e32 v106, v184, v110
	v_mul_f32_e32 v110, v173, v173
	v_mov_b32_e32 v108, v184
	v_mov_b32_e32 v109, v173
	v_pk_add_f32 v[0:1], v[110:111], v[0:1] op_sel_hi:[0,1]
	v_pk_fma_f32 v[0:1], v[108:109], v[108:109], v[0:1]
	v_pk_mul_f32 v[108:109], v[184:185], v[184:185]
	v_pk_mov_b32 v[0:1], v[184:185], v[0:1] op_sel:[1,0]
	v_mov_b32_e32 v107, v109
	v_pk_add_f32 v[0:1], v[0:1], v[106:107]
	v_mov_b32_e32 v106, v0
	v_mov_b32_e32 v107, v1
	s_nop 1
	v_permlane16_swap_b32_e32 v106, v0
	v_permlane16_swap_b32_e32 v107, v1
	s_waitcnt lgkmcnt(0)
	v_pk_add_f32 v[106:107], v[0:1], v[106:107]
	v_mov_b32_e32 v108, v106
	v_mov_b32_e32 v109, v107
	s_nop 1
	v_permlane32_swap_b32_e32 v108, v106
	v_permlane32_swap_b32_e32 v109, v107
	s_and_saveexec_b64 s[0:1], vcc
	s_cbranch_execz .LBB0_749
	s_waitcnt lgkmcnt(0)
	v_pk_add_f32 v[0:1], v[106:107], v[108:109]
	ds_write_b64 v217, v[0:1] offset:256
.LBB0_749:
	s_or_b64 exec, exec, s[0:1]
	v_add_u32_e32 v0, 48, v150
	v_ashrrev_i32_e32 v1, 31, v0
	v_lshlrev_b64 v[198:199], 11, v[0:1]
	v_lshl_add_u64 v[0:1], s[16:17], 0, v[198:199]
	v_lshl_add_u64 v[0:1], v[146:147], 1, v[0:1]
	s_waitcnt lgkmcnt(0)
	s_nop 0
	v_mul_f32_e32 v0, 0xbfb8aa3b, v102
	v_mul_f32_e32 v1, 0xbfb8aa3b, v103
	v_exp_f32_e32 v0, v0
	v_exp_f32_e32 v1, v1
	v_mul_f32_e32 v98, 0xbfb8aa3b, v98
	v_mul_f32_e32 v99, 0xbfb8aa3b, v99
	v_add_f32_e32 v0, 1.0, v0
	v_add_f32_e32 v1, 1.0, v1
	v_rcp_f32_e32 v0, v0
	v_rcp_f32_e32 v1, v1
	v_exp_f32_e32 v98, v98
	v_exp_f32_e32 v99, v99
	v_add_f32_e32 v98, 1.0, v98
	v_add_f32_e32 v99, 1.0, v99
	v_rcp_f32_e32 v98, v98
	v_rcp_f32_e32 v99, v99
	s_waitcnt vmcnt(4)
	v_lshlrev_b32_e32 v102, 16, v232
	v_and_b32_e32 v103, 0xffff0000, v232
	v_pk_mul_f32 v[114:115], v[0:1], v[102:103]
	v_mul_f32_e32 v1, 0xbfb8aa3b, v105
	v_add_f32_e32 v0, 0, v114
	v_add_f32_e32 v106, v115, v0
	v_mul_f32_e32 v0, 0xbfb8aa3b, v104
	v_exp_f32_e32 v0, v0
	v_exp_f32_e32 v1, v1
	v_lshlrev_b32_e32 v102, 16, v233
	v_and_b32_e32 v103, 0xffff0000, v233
	v_add_f32_e32 v0, 1.0, v0
	v_add_f32_e32 v1, 1.0, v1
	v_rcp_f32_e32 v0, v0
	v_rcp_f32_e32 v1, v1
	s_nop 0
	v_pk_mul_f32 v[116:117], v[0:1], v[102:103]
	v_mul_f32_e32 v102, v114, v114
	v_add_f32_e32 v103, v116, v106
	v_mov_b32_e32 v0, v116
	v_mov_b32_e32 v1, v114
	v_fmac_f32_e32 v102, v115, v115
	v_pk_fma_f32 v[0:1], v[0:1], v[0:1], v[102:103] op_sel_hi:[1,1,0]
	v_add_f32_e32 v104, v117, v103
	v_lshlrev_b32_e32 v102, 16, v234
	v_and_b32_e32 v103, 0xffff0000, v234
	v_pk_mul_f32 v[118:119], v[98:99], v[102:103]
	v_mul_f32_e32 v102, v117, v117
	v_add_f32_e32 v103, v118, v104
	v_mov_b32_e32 v98, v118
	v_mov_b32_e32 v99, v117
	v_pk_add_f32 v[0:1], v[102:103], v[0:1] op_sel_hi:[0,1]
	v_pk_fma_f32 v[0:1], v[98:99], v[98:99], v[0:1]
	v_mul_f32_e32 v98, 0xbfb8aa3b, v100
	v_mul_f32_e32 v99, 0xbfb8aa3b, v101
	v_exp_f32_e32 v98, v98
	v_exp_f32_e32 v99, v99
	v_lshlrev_b32_e32 v100, 16, v235
	v_and_b32_e32 v101, 0xffff0000, v235
	v_add_f32_e32 v98, 1.0, v98
	v_add_f32_e32 v99, 1.0, v99
	v_rcp_f32_e32 v98, v98
	v_rcp_f32_e32 v99, v99
	v_add_f32_e32 v102, v119, v103
	v_pk_mul_f32 v[120:121], v[98:99], v[100:101]
	s_nop 0
	v_add_f32_e32 v98, v120, v102
	v_mul_f32_e32 v102, v119, v119
	v_mov_b32_e32 v100, v120
	v_mov_b32_e32 v101, v119
	v_pk_add_f32 v[0:1], v[102:103], v[0:1] op_sel_hi:[0,1]
	v_pk_fma_f32 v[0:1], v[100:101], v[100:101], v[0:1]
	v_pk_mul_f32 v[100:101], v[120:121], v[120:121]
	v_pk_mov_b32 v[0:1], v[120:121], v[0:1] op_sel:[1,0]
	v_mov_b32_e32 v99, v101
	v_pk_add_f32 v[0:1], v[0:1], v[98:99]
	v_mov_b32_e32 v98, v0
	v_mov_b32_e32 v99, v1
	s_nop 1
	v_permlane16_swap_b32_e32 v98, v0
	v_permlane16_swap_b32_e32 v99, v1
	s_waitcnt lgkmcnt(0)
	v_pk_add_f32 v[98:99], v[0:1], v[98:99]
	v_mov_b32_e32 v100, v98
	v_mov_b32_e32 v101, v99
	s_nop 1
	v_permlane32_swap_b32_e32 v100, v98
	v_permlane32_swap_b32_e32 v101, v99
	s_and_saveexec_b64 s[0:1], vcc
	s_cbranch_execz .LBB0_751
	s_waitcnt lgkmcnt(0)
	v_pk_add_f32 v[0:1], v[98:99], v[100:101]
	ds_write_b64 v217, v[0:1] offset:384
.LBB0_751:
	s_or_b64 exec, exec, s[0:1]
	v_add_u32_e32 v0, 0x80, v150
	v_ashrrev_i32_e32 v1, 31, v0
	v_lshlrev_b64 v[200:201], 11, v[0:1]
	v_lshl_add_u64 v[0:1], s[16:17], 0, v[200:201]
	v_lshl_add_u64 v[0:1], v[146:147], 1, v[0:1]
	s_waitcnt lgkmcnt(0)
	s_nop 0
	v_mul_f32_e32 v0, 0xbfb8aa3b, v94
	v_mul_f32_e32 v1, 0xbfb8aa3b, v95
	v_exp_f32_e32 v0, v0
	v_exp_f32_e32 v1, v1
	v_mul_f32_e32 v90, 0xbfb8aa3b, v90
	v_mul_f32_e32 v91, 0xbfb8aa3b, v91
	v_add_f32_e32 v0, 1.0, v0
	v_add_f32_e32 v1, 1.0, v1
	v_rcp_f32_e32 v0, v0
	v_rcp_f32_e32 v1, v1
	v_exp_f32_e32 v90, v90
	v_exp_f32_e32 v91, v91
	v_add_f32_e32 v90, 1.0, v90
	v_add_f32_e32 v91, 1.0, v91
	v_rcp_f32_e32 v90, v90
	v_rcp_f32_e32 v91, v91
	s_waitcnt vmcnt(3)
	v_lshlrev_b32_e32 v94, 16, v236
	v_and_b32_e32 v95, 0xffff0000, v236
	v_pk_mul_f32 v[152:153], v[0:1], v[94:95]
	v_mul_f32_e32 v1, 0xbfb8aa3b, v97
	v_add_f32_e32 v0, 0, v152
	v_add_f32_e32 v98, v153, v0
	v_mul_f32_e32 v0, 0xbfb8aa3b, v96
	v_exp_f32_e32 v0, v0
	v_exp_f32_e32 v1, v1
	v_lshlrev_b32_e32 v94, 16, v237
	v_and_b32_e32 v95, 0xffff0000, v237
	v_add_f32_e32 v0, 1.0, v0
	v_add_f32_e32 v1, 1.0, v1
	v_rcp_f32_e32 v0, v0
	v_rcp_f32_e32 v1, v1
	s_nop 0
	v_pk_mul_f32 v[160:161], v[0:1], v[94:95]
	v_mul_f32_e32 v94, v152, v152
	v_add_f32_e32 v95, v160, v98
	v_mov_b32_e32 v0, v160
	v_mov_b32_e32 v1, v152
	v_fmac_f32_e32 v94, v153, v153
	v_pk_fma_f32 v[0:1], v[0:1], v[0:1], v[94:95] op_sel_hi:[1,1,0]
	v_add_f32_e32 v96, v161, v95
	v_lshlrev_b32_e32 v94, 16, v238
	v_and_b32_e32 v95, 0xffff0000, v238
	v_pk_mul_f32 v[164:165], v[90:91], v[94:95]
	v_mul_f32_e32 v94, v161, v161
	v_add_f32_e32 v95, v164, v96
	v_mov_b32_e32 v90, v164
	v_mov_b32_e32 v91, v161
	v_pk_add_f32 v[0:1], v[94:95], v[0:1] op_sel_hi:[0,1]
	v_pk_fma_f32 v[0:1], v[90:91], v[90:91], v[0:1]
	v_mul_f32_e32 v90, 0xbfb8aa3b, v92
	v_mul_f32_e32 v91, 0xbfb8aa3b, v93
	v_exp_f32_e32 v90, v90
	v_exp_f32_e32 v91, v91
	v_lshlrev_b32_e32 v92, 16, v239
	v_and_b32_e32 v93, 0xffff0000, v239
	v_add_f32_e32 v90, 1.0, v90
	v_add_f32_e32 v91, 1.0, v91
	v_rcp_f32_e32 v90, v90
	v_rcp_f32_e32 v91, v91
	v_add_f32_e32 v94, v165, v95
	v_pk_mul_f32 v[178:179], v[90:91], v[92:93]
	s_nop 0
	v_add_f32_e32 v90, v178, v94
	v_mul_f32_e32 v94, v165, v165
	v_mov_b32_e32 v92, v178
	v_mov_b32_e32 v93, v165
	v_pk_add_f32 v[0:1], v[94:95], v[0:1] op_sel_hi:[0,1]
	v_pk_fma_f32 v[0:1], v[92:93], v[92:93], v[0:1]
	v_pk_mul_f32 v[92:93], v[178:179], v[178:179]
	v_pk_mov_b32 v[0:1], v[178:179], v[0:1] op_sel:[1,0]
	v_mov_b32_e32 v91, v93
	v_pk_add_f32 v[0:1], v[0:1], v[90:91]
	v_mov_b32_e32 v90, v0
	v_mov_b32_e32 v91, v1
	s_nop 1
	v_permlane16_swap_b32_e32 v90, v0
	v_permlane16_swap_b32_e32 v91, v1
	s_waitcnt lgkmcnt(0)
	v_pk_add_f32 v[90:91], v[0:1], v[90:91]
	v_mov_b32_e32 v92, v90
	v_mov_b32_e32 v93, v91
	s_nop 1
	v_permlane32_swap_b32_e32 v92, v90
	v_permlane32_swap_b32_e32 v93, v91
	s_and_saveexec_b64 s[0:1], vcc
	s_cbranch_execz .LBB0_753
	s_waitcnt lgkmcnt(0)
	v_pk_add_f32 v[0:1], v[90:91], v[92:93]
	ds_write_b64 v217, v[0:1] offset:512
.LBB0_753:
	s_or_b64 exec, exec, s[0:1]
	v_add_u32_e32 v0, 0x90, v150
	v_ashrrev_i32_e32 v1, 31, v0
	v_lshlrev_b64 v[94:95], 11, v[0:1]
	v_lshl_add_u64 v[0:1], s[16:17], 0, v[94:95]
	v_lshl_add_u64 v[0:1], v[146:147], 1, v[0:1]
	s_waitcnt lgkmcnt(0)
	s_nop 0
	v_mul_f32_e32 v0, 0xbfb8aa3b, v86
	v_mul_f32_e32 v1, 0xbfb8aa3b, v87
	v_exp_f32_e32 v0, v0
	v_exp_f32_e32 v1, v1
	v_mul_f32_e32 v82, 0xbfb8aa3b, v82
	v_mul_f32_e32 v83, 0xbfb8aa3b, v83
	v_add_f32_e32 v0, 1.0, v0
	v_add_f32_e32 v1, 1.0, v1
	v_rcp_f32_e32 v0, v0
	v_rcp_f32_e32 v1, v1
	v_exp_f32_e32 v82, v82
	v_exp_f32_e32 v83, v83
	v_add_f32_e32 v82, 1.0, v82
	v_add_f32_e32 v83, 1.0, v83
	v_rcp_f32_e32 v82, v82
	v_rcp_f32_e32 v83, v83
	s_waitcnt vmcnt(2)
	v_lshlrev_b32_e32 v86, 16, v242
	v_and_b32_e32 v87, 0xffff0000, v242
	v_pk_mul_f32 v[170:171], v[0:1], v[86:87]
	v_mul_f32_e32 v1, 0xbfb8aa3b, v89
	v_add_f32_e32 v0, 0, v170
	v_add_f32_e32 v90, v171, v0
	v_mul_f32_e32 v0, 0xbfb8aa3b, v88
	v_exp_f32_e32 v0, v0
	v_exp_f32_e32 v1, v1
	v_lshlrev_b32_e32 v86, 16, v243
	v_and_b32_e32 v87, 0xffff0000, v243
	v_add_f32_e32 v0, 1.0, v0
	v_add_f32_e32 v1, 1.0, v1
	v_rcp_f32_e32 v0, v0
	v_rcp_f32_e32 v1, v1
	s_nop 0
	v_pk_mul_f32 v[176:177], v[0:1], v[86:87]
	v_mul_f32_e32 v86, v170, v170
	v_add_f32_e32 v87, v176, v90
	v_mov_b32_e32 v0, v176
	v_mov_b32_e32 v1, v170
	v_fmac_f32_e32 v86, v171, v171
	v_pk_fma_f32 v[0:1], v[0:1], v[0:1], v[86:87] op_sel_hi:[1,1,0]
	v_add_f32_e32 v88, v177, v87
	v_lshlrev_b32_e32 v86, 16, v244
	v_and_b32_e32 v87, 0xffff0000, v244
	v_pk_mul_f32 v[180:181], v[82:83], v[86:87]
	v_mul_f32_e32 v86, v177, v177
	v_add_f32_e32 v87, v180, v88
	v_mov_b32_e32 v82, v180
	v_mov_b32_e32 v83, v177
	v_pk_add_f32 v[0:1], v[86:87], v[0:1] op_sel_hi:[0,1]
	v_pk_fma_f32 v[0:1], v[82:83], v[82:83], v[0:1]
	v_mul_f32_e32 v82, 0xbfb8aa3b, v84
	v_mul_f32_e32 v83, 0xbfb8aa3b, v85
	v_exp_f32_e32 v82, v82
	v_exp_f32_e32 v83, v83
	v_lshlrev_b32_e32 v84, 16, v245
	v_and_b32_e32 v85, 0xffff0000, v245
	v_add_f32_e32 v82, 1.0, v82
	v_add_f32_e32 v83, 1.0, v83
	v_rcp_f32_e32 v82, v82
	v_rcp_f32_e32 v83, v83
	v_add_f32_e32 v86, v181, v87
	v_pk_mul_f32 v[190:191], v[82:83], v[84:85]
	s_nop 0
	v_add_f32_e32 v82, v190, v86
	v_mul_f32_e32 v86, v181, v181
	v_mov_b32_e32 v84, v190
	v_mov_b32_e32 v85, v181
	v_pk_add_f32 v[0:1], v[86:87], v[0:1] op_sel_hi:[0,1]
	v_pk_fma_f32 v[0:1], v[84:85], v[84:85], v[0:1]
	v_pk_mul_f32 v[84:85], v[190:191], v[190:191]
	v_pk_mov_b32 v[0:1], v[190:191], v[0:1] op_sel:[1,0]
	v_mov_b32_e32 v83, v85
	v_pk_add_f32 v[0:1], v[0:1], v[82:83]
	v_mov_b32_e32 v82, v0
	v_mov_b32_e32 v83, v1
	s_nop 1
	v_permlane16_swap_b32_e32 v82, v0
	v_permlane16_swap_b32_e32 v83, v1
	s_waitcnt lgkmcnt(0)
	v_pk_add_f32 v[82:83], v[0:1], v[82:83]
	v_mov_b32_e32 v84, v82
	v_mov_b32_e32 v85, v83
	s_nop 1
	v_permlane32_swap_b32_e32 v84, v82
	v_permlane32_swap_b32_e32 v85, v83
	s_and_saveexec_b64 s[0:1], vcc
	s_cbranch_execz .LBB0_755
	s_waitcnt lgkmcnt(0)
	v_pk_add_f32 v[0:1], v[82:83], v[84:85]
	ds_write_b64 v217, v[0:1] offset:640
.LBB0_755:
	s_or_b64 exec, exec, s[0:1]
	v_add_u32_e32 v0, 0xa0, v150
	v_ashrrev_i32_e32 v1, 31, v0
	v_lshlrev_b64 v[86:87], 11, v[0:1]
	v_lshl_add_u64 v[0:1], s[16:17], 0, v[86:87]
	v_lshl_add_u64 v[0:1], v[146:147], 1, v[0:1]
	s_waitcnt lgkmcnt(0)
	s_nop 0
	v_mul_f32_e32 v0, 0xbfb8aa3b, v78
	v_mul_f32_e32 v1, 0xbfb8aa3b, v79
	v_exp_f32_e32 v0, v0
	v_exp_f32_e32 v1, v1
	v_mul_f32_e32 v74, 0xbfb8aa3b, v74
	v_mul_f32_e32 v75, 0xbfb8aa3b, v75
	v_add_f32_e32 v0, 1.0, v0
	v_add_f32_e32 v1, 1.0, v1
	v_rcp_f32_e32 v0, v0
	v_rcp_f32_e32 v1, v1
	v_exp_f32_e32 v74, v74
	v_exp_f32_e32 v75, v75
	v_add_f32_e32 v74, 1.0, v74
	v_add_f32_e32 v75, 1.0, v75
	v_rcp_f32_e32 v74, v74
	v_rcp_f32_e32 v75, v75
	s_waitcnt vmcnt(1)
	v_lshlrev_b32_e32 v78, 16, v246
	v_and_b32_e32 v79, 0xffff0000, v246
	v_pk_mul_f32 v[182:183], v[0:1], v[78:79]
	v_mul_f32_e32 v1, 0xbfb8aa3b, v81
	v_add_f32_e32 v0, 0, v182
	v_add_f32_e32 v82, v183, v0
	v_mul_f32_e32 v0, 0xbfb8aa3b, v80
	v_exp_f32_e32 v0, v0
	v_exp_f32_e32 v1, v1
	v_lshlrev_b32_e32 v78, 16, v247
	v_and_b32_e32 v79, 0xffff0000, v247
	v_add_f32_e32 v0, 1.0, v0
	v_add_f32_e32 v1, 1.0, v1
	v_rcp_f32_e32 v0, v0
	v_rcp_f32_e32 v1, v1
	s_nop 0
	v_pk_mul_f32 v[186:187], v[0:1], v[78:79]
	v_mul_f32_e32 v78, v182, v182
	v_add_f32_e32 v79, v186, v82
	v_mov_b32_e32 v0, v186
	v_mov_b32_e32 v1, v182
	v_fmac_f32_e32 v78, v183, v183
	v_pk_fma_f32 v[0:1], v[0:1], v[0:1], v[78:79] op_sel_hi:[1,1,0]
	v_add_f32_e32 v80, v187, v79
	v_lshlrev_b32_e32 v78, 16, v248
	v_and_b32_e32 v79, 0xffff0000, v248
	v_pk_mul_f32 v[188:189], v[74:75], v[78:79]
	v_mul_f32_e32 v78, v187, v187
	v_add_f32_e32 v79, v188, v80
	v_mov_b32_e32 v74, v188
	v_mov_b32_e32 v75, v187
	v_pk_add_f32 v[0:1], v[78:79], v[0:1] op_sel_hi:[0,1]
	v_pk_fma_f32 v[0:1], v[74:75], v[74:75], v[0:1]
	v_mul_f32_e32 v74, 0xbfb8aa3b, v76
	v_mul_f32_e32 v75, 0xbfb8aa3b, v77
	v_exp_f32_e32 v74, v74
	v_exp_f32_e32 v75, v75
	v_lshlrev_b32_e32 v76, 16, v249
	v_and_b32_e32 v77, 0xffff0000, v249
	v_add_f32_e32 v74, 1.0, v74
	v_add_f32_e32 v75, 1.0, v75
	v_rcp_f32_e32 v74, v74
	v_rcp_f32_e32 v75, v75
	v_add_f32_e32 v78, v189, v79
	v_pk_mul_f32 v[194:195], v[74:75], v[76:77]
	s_nop 0
	v_add_f32_e32 v74, v194, v78
	v_mul_f32_e32 v78, v189, v189
	v_mov_b32_e32 v76, v194
	v_mov_b32_e32 v77, v189
	v_pk_add_f32 v[0:1], v[78:79], v[0:1] op_sel_hi:[0,1]
	v_pk_fma_f32 v[0:1], v[76:77], v[76:77], v[0:1]
	v_pk_mul_f32 v[76:77], v[194:195], v[194:195]
	v_pk_mov_b32 v[0:1], v[194:195], v[0:1] op_sel:[1,0]
	v_mov_b32_e32 v75, v77
	v_pk_add_f32 v[0:1], v[0:1], v[74:75]
	v_mov_b32_e32 v74, v0
	v_mov_b32_e32 v75, v1
	s_nop 1
	v_permlane16_swap_b32_e32 v74, v0
	v_permlane16_swap_b32_e32 v75, v1
	s_waitcnt lgkmcnt(0)
	v_pk_add_f32 v[74:75], v[0:1], v[74:75]
	v_mov_b32_e32 v76, v74
	v_mov_b32_e32 v77, v75
	s_nop 1
	v_permlane32_swap_b32_e32 v76, v74
	v_permlane32_swap_b32_e32 v77, v75
	s_and_saveexec_b64 s[0:1], vcc
	s_cbranch_execz .LBB0_757
	s_waitcnt lgkmcnt(0)
	v_pk_add_f32 v[0:1], v[74:75], v[76:77]
	ds_write_b64 v217, v[0:1] offset:768
.LBB0_757:
	s_or_b64 exec, exec, s[0:1]
	v_add_u32_e32 v0, 0xb0, v150
	v_ashrrev_i32_e32 v1, 31, v0
	v_lshlrev_b64 v[78:79], 11, v[0:1]
	v_lshl_add_u64 v[0:1], s[16:17], 0, v[78:79]
	v_lshl_add_u64 v[0:1], v[146:147], 1, v[0:1]
	s_waitcnt lgkmcnt(0)
	s_nop 0
	v_mul_f32_e32 v0, 0xbfb8aa3b, v70
	v_mul_f32_e32 v1, 0xbfb8aa3b, v71
	v_exp_f32_e32 v0, v0
	v_exp_f32_e32 v1, v1
	v_mul_f32_e32 v66, 0xbfb8aa3b, v66
	v_mul_f32_e32 v67, 0xbfb8aa3b, v67
	v_add_f32_e32 v0, 1.0, v0
	v_add_f32_e32 v1, 1.0, v1
	v_rcp_f32_e32 v0, v0
	v_rcp_f32_e32 v1, v1
	v_exp_f32_e32 v66, v66
	v_exp_f32_e32 v67, v67
	v_add_f32_e32 v66, 1.0, v66
	v_add_f32_e32 v67, 1.0, v67
	v_rcp_f32_e32 v66, v66
	v_rcp_f32_e32 v67, v67
	s_waitcnt vmcnt(0)
	v_lshlrev_b32_e32 v70, 16, v250
	v_and_b32_e32 v71, 0xffff0000, v250
	v_pk_mul_f32 v[122:123], v[0:1], v[70:71]
	v_mul_f32_e32 v1, 0xbfb8aa3b, v73
	v_add_f32_e32 v0, 0, v122
	v_add_f32_e32 v74, v123, v0
	v_mul_f32_e32 v0, 0xbfb8aa3b, v72
	v_exp_f32_e32 v0, v0
	v_exp_f32_e32 v1, v1
	v_lshlrev_b32_e32 v70, 16, v251
	v_and_b32_e32 v71, 0xffff0000, v251
	v_add_f32_e32 v0, 1.0, v0
	v_add_f32_e32 v1, 1.0, v1
	v_rcp_f32_e32 v0, v0
	v_rcp_f32_e32 v1, v1
	s_nop 0
	v_pk_mul_f32 v[124:125], v[0:1], v[70:71]
	v_mul_f32_e32 v70, v122, v122
	v_add_f32_e32 v71, v124, v74
	v_mov_b32_e32 v0, v124
	v_mov_b32_e32 v1, v122
	v_fmac_f32_e32 v70, v123, v123
	v_pk_fma_f32 v[0:1], v[0:1], v[0:1], v[70:71] op_sel_hi:[1,1,0]
	v_add_f32_e32 v72, v125, v71
	v_lshlrev_b32_e32 v70, 16, v252
	v_and_b32_e32 v71, 0xffff0000, v252
	v_pk_mul_f32 v[150:151], v[66:67], v[70:71]
	v_mul_f32_e32 v70, v125, v125
	v_add_f32_e32 v71, v150, v72
	v_mov_b32_e32 v66, v150
	v_mov_b32_e32 v67, v125
	v_pk_add_f32 v[0:1], v[70:71], v[0:1] op_sel_hi:[0,1]
	v_pk_fma_f32 v[0:1], v[66:67], v[66:67], v[0:1]
	v_mul_f32_e32 v66, 0xbfb8aa3b, v68
	v_mul_f32_e32 v67, 0xbfb8aa3b, v69
	v_exp_f32_e32 v66, v66
	v_exp_f32_e32 v67, v67
	v_lshlrev_b32_e32 v68, 16, v253
	v_and_b32_e32 v69, 0xffff0000, v253
	v_add_f32_e32 v66, 1.0, v66
	v_add_f32_e32 v67, 1.0, v67
	v_rcp_f32_e32 v66, v66
	v_rcp_f32_e32 v67, v67
	v_add_f32_e32 v70, v151, v71
	v_pk_mul_f32 v[168:169], v[66:67], v[68:69]
	s_nop 0
	v_add_f32_e32 v66, v168, v70
	v_mul_f32_e32 v70, v151, v151
	v_mov_b32_e32 v68, v168
	v_mov_b32_e32 v69, v151
	v_pk_add_f32 v[0:1], v[70:71], v[0:1] op_sel_hi:[0,1]
	v_pk_fma_f32 v[0:1], v[68:69], v[68:69], v[0:1]
	v_pk_mul_f32 v[68:69], v[168:169], v[168:169]
	v_pk_mov_b32 v[0:1], v[168:169], v[0:1] op_sel:[1,0]
	v_mov_b32_e32 v67, v69
	v_pk_add_f32 v[0:1], v[0:1], v[66:67]
	v_mov_b32_e32 v66, v0
	v_mov_b32_e32 v67, v1
	s_nop 1
	v_permlane16_swap_b32_e32 v66, v0
	v_permlane16_swap_b32_e32 v67, v1
	s_waitcnt lgkmcnt(0)
	v_pk_add_f32 v[66:67], v[0:1], v[66:67]
	v_mov_b32_e32 v68, v66
	v_mov_b32_e32 v69, v67
	s_nop 1
	v_permlane32_swap_b32_e32 v68, v66
	v_permlane32_swap_b32_e32 v69, v67
	s_and_saveexec_b64 s[0:1], vcc
	s_cbranch_execz .LBB0_759
	s_waitcnt lgkmcnt(0)
	v_pk_add_f32 v[0:1], v[66:67], v[68:69]
	ds_write_b64 v217, v[0:1] offset:896

.LBB0_1594:
	s_lshl_b32 s6, s68, 7
	s_or_b32 s6, s6, s77
	s_lshl_b32 s24, s70, 8
	v_lshl_add_u32 v142, v148, 3, s6
	s_add_i32 s6, s24, s76
	v_add_u32_e32 v180, s6, v214
	v_ashrrev_i32_e32 v181, 31, v180
	v_lshlrev_b64 v[192:193], 11, v[180:181]
	v_ashrrev_i32_e32 v143, 31, v142
	v_lshl_add_u64 v[0:1], s[10:11], 0, v[192:193]
	v_lshl_add_u64 v[0:1], v[142:143], 1, v[0:1]
	global_load_dwordx4 v[220:223], v[0:1], off
	v_add_u32_e32 v224, 16, v180
	v_ashrrev_i32_e32 v225, 31, v224
	v_lshlrev_b64 v[224:225], 11, v[224:225]
	v_lshl_add_u64 v[224:225], s[10:11], 0, v[224:225]
	v_lshl_add_u64 v[224:225], v[142:143], 1, v[224:225]
	global_load_dwordx4 v[224:227], v[224:225], off
	v_add_u32_e32 v228, 32, v180
	v_ashrrev_i32_e32 v229, 31, v228
	v_lshlrev_b64 v[228:229], 11, v[228:229]
	v_lshl_add_u64 v[228:229], s[10:11], 0, v[228:229]
	v_lshl_add_u64 v[228:229], v[142:143], 1, v[228:229]
	global_load_dwordx4 v[228:231], v[228:229], off
	v_add_u32_e32 v232, 48, v180
	v_ashrrev_i32_e32 v233, 31, v232
	v_lshlrev_b64 v[232:233], 11, v[232:233]
	v_lshl_add_u64 v[232:233], s[10:11], 0, v[232:233]
	v_lshl_add_u64 v[232:233], v[142:143], 1, v[232:233]
	global_load_dwordx4 v[232:235], v[232:233], off
	v_add_u32_e32 v236, 128, v180
	v_ashrrev_i32_e32 v237, 31, v236
	v_lshlrev_b64 v[236:237], 11, v[236:237]
	v_lshl_add_u64 v[236:237], s[10:11], 0, v[236:237]
	v_lshl_add_u64 v[236:237], v[142:143], 1, v[236:237]
	global_load_dwordx4 v[236:239], v[236:237], off
	v_add_u32_e32 v242, 144, v180
	v_ashrrev_i32_e32 v243, 31, v242
	v_lshlrev_b64 v[242:243], 11, v[242:243]
	v_lshl_add_u64 v[242:243], s[10:11], 0, v[242:243]
	v_lshl_add_u64 v[242:243], v[142:143], 1, v[242:243]
	global_load_dwordx4 v[242:245], v[242:243], off
	v_add_u32_e32 v246, 160, v180
	v_ashrrev_i32_e32 v247, 31, v246
	v_lshlrev_b64 v[246:247], 11, v[246:247]
	v_lshl_add_u64 v[246:247], s[10:11], 0, v[246:247]
	v_lshl_add_u64 v[246:247], v[142:143], 1, v[246:247]
	global_load_dwordx4 v[246:249], v[246:247], off
	v_add_u32_e32 v250, 176, v180
	v_ashrrev_i32_e32 v251, 31, v250
	v_lshlrev_b64 v[250:251], 11, v[250:251]
	v_lshl_add_u64 v[250:251], s[10:11], 0, v[250:251]
	v_lshl_add_u64 v[250:251], v[142:143], 1, v[250:251]
	global_load_dwordx4 v[250:253], v[250:251], off
	v_and_b32_e32 v1, 64, v211
	v_mul_f32_e32 v126, 0xbfb8aa3b, v126
	v_mul_f32_e32 v127, 0xbfb8aa3b, v127
	v_mul_f32_e32 v128, 0xbfb8aa3b, v128
	v_mul_f32_e32 v129, 0xbfb8aa3b, v129
	v_add_u32_e32 v149, 64, v1
	v_exp_f32_e32 v1, v126
	v_exp_f32_e32 v126, v127
	v_xor_b32_e32 v0, 16, v211
	v_mul_f32_e32 v122, 0xbfb8aa3b, v122
	v_mul_f32_e32 v123, 0xbfb8aa3b, v123
	v_exp_f32_e32 v127, v128
	v_exp_f32_e32 v128, v129
	v_exp_f32_e32 v122, v122
	v_exp_f32_e32 v123, v123
	v_cmp_lt_i32_e32 vcc, v0, v149
	v_mul_f32_e32 v124, 0xbfb8aa3b, v124
	v_mul_f32_e32 v125, 0xbfb8aa3b, v125
	v_cndmask_b32_e32 v0, v211, v0, vcc
	v_exp_f32_e32 v124, v124
	v_exp_f32_e32 v125, v125
	v_lshlrev_b32_e32 v215, 2, v0
	v_add_f32_e32 v0, 1.0, v1
	v_add_f32_e32 v1, 1.0, v126
	v_add_f32_e32 v126, 1.0, v127
	v_add_f32_e32 v127, 1.0, v128
	v_rcp_f32_e32 v0, v0
	v_rcp_f32_e32 v1, v1
	v_add_f32_e32 v128, 1.0, v122
	v_add_f32_e32 v129, 1.0, v123
	v_rcp_f32_e32 v122, v126
	v_rcp_f32_e32 v123, v127
	v_add_f32_e32 v150, 1.0, v124
	v_add_f32_e32 v151, 1.0, v125
	v_rcp_f32_e32 v124, v128
	v_rcp_f32_e32 v125, v129
	v_rcp_f32_e32 v150, v150
	v_rcp_f32_e32 v151, v151
	s_waitcnt vmcnt(7)
	v_lshlrev_b32_e32 v126, 16, v220
	v_and_b32_e32 v127, 0xffff0000, v220
	v_lshlrev_b32_e32 v144, 16, v221
	v_and_b32_e32 v145, 0xffff0000, v221
	v_pk_mul_f32 v[128:129], v[0:1], v[126:127]
	v_pk_mul_f32 v[126:127], v[122:123], v[144:145]
	v_add_f32_e32 v145, 0, v128
	v_mul_f32_e32 v144, v128, v128
	v_add_f32_e32 v145, v129, v145
	v_lshlrev_b32_e32 v152, 16, v222
	v_and_b32_e32 v153, 0xffff0000, v222
	v_lshlrev_b32_e32 v146, 16, v223
	v_and_b32_e32 v147, 0xffff0000, v223
	v_mov_b32_e32 v0, v126
	v_mov_b32_e32 v1, v128
	v_fmac_f32_e32 v144, v129, v129
	v_add_f32_e32 v145, v126, v145
	v_pk_mul_f32 v[124:125], v[124:125], v[152:153]
	v_pk_mul_f32 v[122:123], v[150:151], v[146:147]
	v_mul_f32_e32 v150, v127, v127
	v_pk_fma_f32 v[0:1], v[0:1], v[0:1], v[144:145] op_sel_hi:[1,1,0]
	v_mov_b32_e32 v146, v124
	v_mov_b32_e32 v147, v127
	v_pk_add_f32 v[0:1], v[150:151], v[0:1] op_sel_hi:[0,1]
	v_mul_f32_e32 v154, v125, v125
	v_add_f32_e32 v144, v127, v145
	v_pk_fma_f32 v[0:1], v[146:147], v[146:147], v[0:1]
	v_mov_b32_e32 v152, v122
	v_mov_b32_e32 v153, v125
	v_add_f32_e32 v144, v124, v144
	v_pk_add_f32 v[0:1], v[154:155], v[0:1] op_sel_hi:[0,1]
	v_pk_mul_f32 v[156:157], v[122:123], v[122:123]
	v_add_f32_e32 v144, v125, v144
	v_pk_fma_f32 v[0:1], v[152:153], v[152:153], v[0:1]
	v_add_f32_e32 v156, v122, v144
	v_pk_mov_b32 v[0:1], v[122:123], v[0:1] op_sel:[1,0]
	v_xor_b32_e32 v146, 32, v211
	v_pk_add_f32 v[0:1], v[0:1], v[156:157]
	v_mov_b32_e32 v144, v0
	v_mov_b32_e32 v145, v1
	s_nop 1
	v_permlane16_swap_b32_e32 v144, v0
	v_permlane16_swap_b32_e32 v145, v1
	v_cmp_lt_i32_e32 vcc, v146, v149
	v_add_u32_e32 v150, s80, v214
	s_waitcnt lgkmcnt(0)
	v_pk_add_f32 v[144:145], v[0:1], v[144:145]
	v_cndmask_b32_e32 v146, v211, v146, vcc
	v_lshlrev_b32_e32 v216, 2, v146
	v_mov_b32_e32 v146, v144
	v_mov_b32_e32 v147, v145
	s_nop 1
	v_permlane32_swap_b32_e32 v146, v144
	v_permlane32_swap_b32_e32 v147, v145
	v_cmp_eq_u32_e32 vcc, 0, v148
	s_and_saveexec_b64 s[6:7], vcc
	s_cbranch_execz .LBB0_1596
	v_lshl_add_u32 v0, v150, 3, 0
	v_add_u32_e32 v148, 0x20000, v0
	s_waitcnt lgkmcnt(0)
	v_pk_add_f32 v[0:1], v[144:145], v[146:147]
	ds_write_b64 v148, v[0:1]
.LBB0_1596:
	s_or_b64 exec, exec, s[6:7]
	v_add_u32_e32 v0, 16, v180
	v_ashrrev_i32_e32 v1, 31, v0
	v_lshlrev_b64 v[194:195], 11, v[0:1]
	v_lshl_add_u64 v[0:1], s[10:11], 0, v[194:195]
	v_lshl_add_u64 v[0:1], v[142:143], 1, v[0:1]
	s_waitcnt lgkmcnt(0)
	s_nop 0
	v_mul_f32_e32 v0, 0xbfb8aa3b, v118
	v_mul_f32_e32 v1, 0xbfb8aa3b, v119
	v_mul_f32_e32 v118, 0xbfb8aa3b, v120
	v_mul_f32_e32 v119, 0xbfb8aa3b, v121
	v_exp_f32_e32 v0, v0
	v_exp_f32_e32 v1, v1
	v_mul_f32_e32 v114, 0xbfb8aa3b, v114
	v_mul_f32_e32 v115, 0xbfb8aa3b, v115
	v_exp_f32_e32 v118, v118
	v_exp_f32_e32 v119, v119
	v_exp_f32_e32 v114, v114
	v_exp_f32_e32 v115, v115
	v_mul_f32_e32 v116, 0xbfb8aa3b, v116
	v_mul_f32_e32 v117, 0xbfb8aa3b, v117
	v_exp_f32_e32 v116, v116
	v_exp_f32_e32 v117, v117
	v_add_f32_e32 v0, 1.0, v0
	v_add_f32_e32 v1, 1.0, v1
	v_add_f32_e32 v118, 1.0, v118
	v_add_f32_e32 v119, 1.0, v119
	v_rcp_f32_e32 v0, v0
	v_rcp_f32_e32 v1, v1
	v_add_f32_e32 v120, 1.0, v114
	v_add_f32_e32 v121, 1.0, v115
	v_rcp_f32_e32 v114, v118
	v_rcp_f32_e32 v115, v119
	v_add_f32_e32 v148, 1.0, v116
	v_add_f32_e32 v149, 1.0, v117
	v_rcp_f32_e32 v116, v120
	v_rcp_f32_e32 v117, v121
	v_rcp_f32_e32 v118, v148
	v_rcp_f32_e32 v119, v149
	v_lshl_add_u32 v217, v150, 3, s81
	s_waitcnt vmcnt(6)
	v_lshlrev_b32_e32 v120, 16, v224
	v_and_b32_e32 v121, 0xffff0000, v224
	v_lshlrev_b32_e32 v144, 16, v225
	v_and_b32_e32 v145, 0xffff0000, v225
	v_pk_mul_f32 v[152:153], v[0:1], v[120:121]
	v_pk_mul_f32 v[148:149], v[114:115], v[144:145]
	v_add_f32_e32 v115, 0, v152
	v_mul_f32_e32 v114, v152, v152
	v_add_f32_e32 v115, v153, v115
	v_lshlrev_b32_e32 v154, 16, v226
	v_and_b32_e32 v155, 0xffff0000, v226
	v_lshlrev_b32_e32 v156, 16, v227
	v_and_b32_e32 v157, 0xffff0000, v227
	v_mov_b32_e32 v0, v148
	v_mov_b32_e32 v1, v152
	v_fmac_f32_e32 v114, v153, v153
	v_add_f32_e32 v115, v148, v115
	v_pk_mul_f32 v[146:147], v[116:117], v[154:155]
	v_pk_mul_f32 v[144:145], v[118:119], v[156:157]
	v_mul_f32_e32 v118, v149, v149
	v_pk_fma_f32 v[0:1], v[0:1], v[0:1], v[114:115] op_sel_hi:[1,1,0]
	v_mov_b32_e32 v116, v146
	v_mov_b32_e32 v117, v149
	v_pk_add_f32 v[0:1], v[118:119], v[0:1] op_sel_hi:[0,1]
	v_mul_f32_e32 v154, v147, v147
	v_add_f32_e32 v114, v149, v115
	v_pk_fma_f32 v[0:1], v[116:117], v[116:117], v[0:1]
	v_mov_b32_e32 v120, v144
	v_mov_b32_e32 v121, v147
	v_add_f32_e32 v114, v146, v114
	v_pk_add_f32 v[0:1], v[154:155], v[0:1] op_sel_hi:[0,1]
	v_pk_mul_f32 v[156:157], v[144:145], v[144:145]
	v_add_f32_e32 v114, v147, v114
	v_pk_fma_f32 v[0:1], v[120:121], v[120:121], v[0:1]
	v_add_f32_e32 v156, v144, v114
	v_pk_mov_b32 v[0:1], v[144:145], v[0:1] op_sel:[1,0]
	s_nop 0
	v_pk_add_f32 v[0:1], v[0:1], v[156:157]
	v_mov_b32_e32 v114, v0
	v_mov_b32_e32 v115, v1
	s_nop 1
	v_permlane16_swap_b32_e32 v114, v0
	v_permlane16_swap_b32_e32 v115, v1
	s_waitcnt lgkmcnt(0)
	v_pk_add_f32 v[114:115], v[0:1], v[114:115]
	v_mov_b32_e32 v116, v114
	v_mov_b32_e32 v117, v115
	s_nop 1
	v_permlane32_swap_b32_e32 v116, v114
	v_permlane32_swap_b32_e32 v117, v115
	s_and_saveexec_b64 s[6:7], vcc
	s_cbranch_execz .LBB0_1598
	s_waitcnt lgkmcnt(0)
	v_pk_add_f32 v[0:1], v[114:115], v[116:117]
	ds_write_b64 v217, v[0:1] offset:128
.LBB0_1598:
	s_or_b64 exec, exec, s[6:7]
	v_add_u32_e32 v0, 32, v180
	v_ashrrev_i32_e32 v1, 31, v0
	v_lshlrev_b64 v[196:197], 11, v[0:1]
	v_lshl_add_u64 v[0:1], s[10:11], 0, v[196:197]
	v_lshl_add_u64 v[0:1], v[142:143], 1, v[0:1]
	s_waitcnt lgkmcnt(0)
	s_nop 0
	v_mul_f32_e32 v0, 0xbfb8aa3b, v110
	v_mul_f32_e32 v1, 0xbfb8aa3b, v111
	v_mul_f32_e32 v110, 0xbfb8aa3b, v112
	v_mul_f32_e32 v111, 0xbfb8aa3b, v113
	v_exp_f32_e32 v0, v0
	v_exp_f32_e32 v1, v1
	v_mul_f32_e32 v106, 0xbfb8aa3b, v106
	v_mul_f32_e32 v107, 0xbfb8aa3b, v107
	v_exp_f32_e32 v110, v110
	v_exp_f32_e32 v111, v111
	v_exp_f32_e32 v106, v106
	v_exp_f32_e32 v107, v107
	v_mul_f32_e32 v108, 0xbfb8aa3b, v108
	v_mul_f32_e32 v109, 0xbfb8aa3b, v109
	v_exp_f32_e32 v108, v108
	v_exp_f32_e32 v109, v109
	v_add_f32_e32 v0, 1.0, v0
	v_add_f32_e32 v1, 1.0, v1
	v_add_f32_e32 v110, 1.0, v110
	v_add_f32_e32 v111, 1.0, v111
	v_rcp_f32_e32 v0, v0
	v_rcp_f32_e32 v1, v1
	v_add_f32_e32 v112, 1.0, v106
	v_add_f32_e32 v113, 1.0, v107
	v_rcp_f32_e32 v106, v110
	v_rcp_f32_e32 v107, v111
	v_add_f32_e32 v118, 1.0, v108
	v_add_f32_e32 v119, 1.0, v109
	v_rcp_f32_e32 v108, v112
	v_rcp_f32_e32 v109, v113
	v_rcp_f32_e32 v110, v118
	v_rcp_f32_e32 v111, v119
	s_waitcnt vmcnt(5)
	v_lshlrev_b32_e32 v112, 16, v228
	v_and_b32_e32 v113, 0xffff0000, v228
	v_lshlrev_b32_e32 v114, 16, v229
	v_and_b32_e32 v115, 0xffff0000, v229
	v_pk_mul_f32 v[168:169], v[0:1], v[112:113]
	v_pk_mul_f32 v[164:165], v[106:107], v[114:115]
	v_add_f32_e32 v107, 0, v168
	v_mul_f32_e32 v106, v168, v168
	v_add_f32_e32 v107, v169, v107
	v_lshlrev_b32_e32 v118, 16, v230
	v_and_b32_e32 v119, 0xffff0000, v230
	v_lshlrev_b32_e32 v116, 16, v231
	v_and_b32_e32 v117, 0xffff0000, v231
	v_mov_b32_e32 v0, v164
	v_mov_b32_e32 v1, v168
	v_fmac_f32_e32 v106, v169, v169
	v_add_f32_e32 v107, v164, v107
	v_pk_mul_f32 v[162:163], v[108:109], v[118:119]
	v_pk_mul_f32 v[160:161], v[110:111], v[116:117]
	v_mul_f32_e32 v110, v165, v165
	v_pk_fma_f32 v[0:1], v[0:1], v[0:1], v[106:107] op_sel_hi:[1,1,0]
	v_mov_b32_e32 v108, v162
	v_mov_b32_e32 v109, v165
	v_pk_add_f32 v[0:1], v[110:111], v[0:1] op_sel_hi:[0,1]
	v_mul_f32_e32 v114, v163, v163
	v_add_f32_e32 v106, v165, v107
	v_pk_fma_f32 v[0:1], v[108:109], v[108:109], v[0:1]
	v_mov_b32_e32 v112, v160
	v_mov_b32_e32 v113, v163
	v_add_f32_e32 v106, v162, v106
	v_pk_add_f32 v[0:1], v[114:115], v[0:1] op_sel_hi:[0,1]
	v_pk_mul_f32 v[116:117], v[160:161], v[160:161]
	v_add_f32_e32 v106, v163, v106
	v_pk_fma_f32 v[0:1], v[112:113], v[112:113], v[0:1]
	v_add_f32_e32 v116, v160, v106
	v_pk_mov_b32 v[0:1], v[160:161], v[0:1] op_sel:[1,0]
	s_nop 0
	v_pk_add_f32 v[0:1], v[0:1], v[116:117]
	v_mov_b32_e32 v106, v0
	v_mov_b32_e32 v107, v1
	s_nop 1
	v_permlane16_swap_b32_e32 v106, v0
	v_permlane16_swap_b32_e32 v107, v1
	s_waitcnt lgkmcnt(0)
	v_pk_add_f32 v[106:107], v[0:1], v[106:107]
	v_mov_b32_e32 v108, v106
	v_mov_b32_e32 v109, v107
	s_nop 1
	v_permlane32_swap_b32_e32 v108, v106
	v_permlane32_swap_b32_e32 v109, v107
	s_and_saveexec_b64 s[6:7], vcc
	s_cbranch_execz .LBB0_1600
	s_waitcnt lgkmcnt(0)
	v_pk_add_f32 v[0:1], v[106:107], v[108:109]
	ds_write_b64 v217, v[0:1] offset:256
.LBB0_1600:
	s_or_b64 exec, exec, s[6:7]
	v_add_u32_e32 v0, 48, v180
	v_ashrrev_i32_e32 v1, 31, v0
	v_lshlrev_b64 v[198:199], 11, v[0:1]
	v_lshl_add_u64 v[0:1], s[10:11], 0, v[198:199]
	v_lshl_add_u64 v[0:1], v[142:143], 1, v[0:1]
	s_waitcnt lgkmcnt(0)
	s_nop 0
	v_mul_f32_e32 v0, 0xbfb8aa3b, v102
	v_mul_f32_e32 v1, 0xbfb8aa3b, v103
	v_mul_f32_e32 v102, 0xbfb8aa3b, v104
	v_mul_f32_e32 v103, 0xbfb8aa3b, v105
	v_exp_f32_e32 v0, v0
	v_exp_f32_e32 v1, v1
	v_mul_f32_e32 v98, 0xbfb8aa3b, v98
	v_mul_f32_e32 v99, 0xbfb8aa3b, v99
	v_exp_f32_e32 v102, v102
	v_exp_f32_e32 v103, v103
	v_exp_f32_e32 v98, v98
	v_exp_f32_e32 v99, v99
	v_mul_f32_e32 v100, 0xbfb8aa3b, v100
	v_mul_f32_e32 v101, 0xbfb8aa3b, v101
	v_exp_f32_e32 v100, v100
	v_exp_f32_e32 v101, v101
	v_add_f32_e32 v0, 1.0, v0
	v_add_f32_e32 v1, 1.0, v1
	v_add_f32_e32 v102, 1.0, v102
	v_add_f32_e32 v103, 1.0, v103
	v_rcp_f32_e32 v0, v0
	v_rcp_f32_e32 v1, v1
	v_add_f32_e32 v104, 1.0, v98
	v_add_f32_e32 v105, 1.0, v99
	v_rcp_f32_e32 v98, v102
	v_rcp_f32_e32 v99, v103
	v_add_f32_e32 v110, 1.0, v100
	v_add_f32_e32 v111, 1.0, v101
	v_rcp_f32_e32 v100, v104
	v_rcp_f32_e32 v101, v105
	v_rcp_f32_e32 v102, v110
	v_rcp_f32_e32 v103, v111
	s_waitcnt vmcnt(4)
	v_lshlrev_b32_e32 v104, 16, v232
	v_and_b32_e32 v105, 0xffff0000, v232
	v_lshlrev_b32_e32 v106, 16, v233
	v_and_b32_e32 v107, 0xffff0000, v233
	v_pk_mul_f32 v[186:187], v[0:1], v[104:105]
	v_pk_mul_f32 v[182:183], v[98:99], v[106:107]
	v_add_f32_e32 v99, 0, v186
	v_mul_f32_e32 v98, v186, v186
	v_add_f32_e32 v99, v187, v99
	v_lshlrev_b32_e32 v110, 16, v234
	v_and_b32_e32 v111, 0xffff0000, v234
	v_lshlrev_b32_e32 v108, 16, v235
	v_and_b32_e32 v109, 0xffff0000, v235
	v_mov_b32_e32 v0, v182
	v_mov_b32_e32 v1, v186
	v_fmac_f32_e32 v98, v187, v187
	v_add_f32_e32 v99, v182, v99
	v_pk_mul_f32 v[178:179], v[100:101], v[110:111]
	v_pk_mul_f32 v[174:175], v[102:103], v[108:109]
	v_mul_f32_e32 v102, v183, v183
	v_pk_fma_f32 v[0:1], v[0:1], v[0:1], v[98:99] op_sel_hi:[1,1,0]
	v_mov_b32_e32 v100, v178
	v_mov_b32_e32 v101, v183
	v_pk_add_f32 v[0:1], v[102:103], v[0:1] op_sel_hi:[0,1]
	v_mul_f32_e32 v106, v179, v179
	v_add_f32_e32 v98, v183, v99
	v_pk_fma_f32 v[0:1], v[100:101], v[100:101], v[0:1]
	v_mov_b32_e32 v104, v174
	v_mov_b32_e32 v105, v179
	v_add_f32_e32 v98, v178, v98
	v_pk_add_f32 v[0:1], v[106:107], v[0:1] op_sel_hi:[0,1]
	v_pk_mul_f32 v[108:109], v[174:175], v[174:175]
	v_add_f32_e32 v98, v179, v98
	v_pk_fma_f32 v[0:1], v[104:105], v[104:105], v[0:1]
	v_add_f32_e32 v108, v174, v98
	v_pk_mov_b32 v[0:1], v[174:175], v[0:1] op_sel:[1,0]
	s_nop 0
	v_pk_add_f32 v[0:1], v[0:1], v[108:109]
	v_mov_b32_e32 v98, v0
	v_mov_b32_e32 v99, v1
	s_nop 1
	v_permlane16_swap_b32_e32 v98, v0
	v_permlane16_swap_b32_e32 v99, v1
	s_waitcnt lgkmcnt(0)
	v_pk_add_f32 v[98:99], v[0:1], v[98:99]
	v_mov_b32_e32 v100, v98
	v_mov_b32_e32 v101, v99
	s_nop 1
	v_permlane32_swap_b32_e32 v100, v98
	v_permlane32_swap_b32_e32 v101, v99
	s_and_saveexec_b64 s[6:7], vcc
	s_cbranch_execz .LBB0_1602
	s_waitcnt lgkmcnt(0)
	v_pk_add_f32 v[0:1], v[98:99], v[100:101]
	ds_write_b64 v217, v[0:1] offset:384
.LBB0_1602:
	s_or_b64 exec, exec, s[6:7]
	v_add_u32_e32 v0, 0x80, v180
	v_ashrrev_i32_e32 v1, 31, v0
	v_lshlrev_b64 v[200:201], 11, v[0:1]
	v_lshl_add_u64 v[0:1], s[10:11], 0, v[200:201]
	v_lshl_add_u64 v[0:1], v[142:143], 1, v[0:1]
	s_waitcnt lgkmcnt(0)
	s_nop 0
	v_mul_f32_e32 v0, 0xbfb8aa3b, v94
	v_mul_f32_e32 v1, 0xbfb8aa3b, v95
	v_mul_f32_e32 v94, 0xbfb8aa3b, v96
	v_mul_f32_e32 v95, 0xbfb8aa3b, v97
	v_exp_f32_e32 v0, v0
	v_exp_f32_e32 v1, v1
	v_mul_f32_e32 v90, 0xbfb8aa3b, v90
	v_mul_f32_e32 v91, 0xbfb8aa3b, v91
	v_exp_f32_e32 v94, v94
	v_exp_f32_e32 v95, v95
	v_exp_f32_e32 v90, v90
	v_exp_f32_e32 v91, v91
	v_mul_f32_e32 v92, 0xbfb8aa3b, v92
	v_mul_f32_e32 v93, 0xbfb8aa3b, v93
	v_exp_f32_e32 v92, v92
	v_exp_f32_e32 v93, v93
	v_add_f32_e32 v0, 1.0, v0
	v_add_f32_e32 v1, 1.0, v1
	v_add_f32_e32 v94, 1.0, v94
	v_add_f32_e32 v95, 1.0, v95
	v_rcp_f32_e32 v0, v0
	v_rcp_f32_e32 v1, v1
	v_add_f32_e32 v96, 1.0, v90
	v_add_f32_e32 v97, 1.0, v91
	v_rcp_f32_e32 v90, v94
	v_rcp_f32_e32 v91, v95
	v_add_f32_e32 v102, 1.0, v92
	v_add_f32_e32 v103, 1.0, v93
	v_rcp_f32_e32 v92, v96
	v_rcp_f32_e32 v93, v97
	v_rcp_f32_e32 v94, v102
	v_rcp_f32_e32 v95, v103
	s_waitcnt vmcnt(3)
	v_lshlrev_b32_e32 v96, 16, v236
	v_and_b32_e32 v97, 0xffff0000, v236
	v_lshlrev_b32_e32 v98, 16, v237
	v_and_b32_e32 v99, 0xffff0000, v237
	v_pk_mul_f32 v[120:121], v[0:1], v[96:97]
	v_pk_mul_f32 v[118:119], v[90:91], v[98:99]
	v_add_f32_e32 v91, 0, v120
	v_mul_f32_e32 v90, v120, v120
	v_add_f32_e32 v91, v121, v91
	v_lshlrev_b32_e32 v102, 16, v238
	v_and_b32_e32 v103, 0xffff0000, v238
	v_lshlrev_b32_e32 v100, 16, v239
	v_and_b32_e32 v101, 0xffff0000, v239
	v_mov_b32_e32 v0, v118
	v_mov_b32_e32 v1, v120
	v_fmac_f32_e32 v90, v121, v121
	v_add_f32_e32 v91, v118, v91
	v_pk_mul_f32 v[116:117], v[92:93], v[102:103]
	v_pk_mul_f32 v[114:115], v[94:95], v[100:101]
	v_mul_f32_e32 v94, v119, v119
	v_pk_fma_f32 v[0:1], v[0:1], v[0:1], v[90:91] op_sel_hi:[1,1,0]
	v_mov_b32_e32 v92, v116
	v_mov_b32_e32 v93, v119
	v_pk_add_f32 v[0:1], v[94:95], v[0:1] op_sel_hi:[0,1]
	v_mul_f32_e32 v98, v117, v117
	v_add_f32_e32 v90, v119, v91
	v_pk_fma_f32 v[0:1], v[92:93], v[92:93], v[0:1]
	v_mov_b32_e32 v96, v114
	v_mov_b32_e32 v97, v117
	v_add_f32_e32 v90, v116, v90
	v_pk_add_f32 v[0:1], v[98:99], v[0:1] op_sel_hi:[0,1]
	v_pk_mul_f32 v[100:101], v[114:115], v[114:115]
	v_add_f32_e32 v90, v117, v90
	v_pk_fma_f32 v[0:1], v[96:97], v[96:97], v[0:1]
	v_add_f32_e32 v100, v114, v90
	v_pk_mov_b32 v[0:1], v[114:115], v[0:1] op_sel:[1,0]
	s_nop 0
	v_pk_add_f32 v[0:1], v[0:1], v[100:101]
	v_mov_b32_e32 v90, v0
	v_mov_b32_e32 v91, v1
	s_nop 1
	v_permlane16_swap_b32_e32 v90, v0
	v_permlane16_swap_b32_e32 v91, v1
	s_waitcnt lgkmcnt(0)
	v_pk_add_f32 v[90:91], v[0:1], v[90:91]
	v_mov_b32_e32 v92, v90
	v_mov_b32_e32 v93, v91
	s_nop 1
	v_permlane32_swap_b32_e32 v92, v90
	v_permlane32_swap_b32_e32 v93, v91
	s_and_saveexec_b64 s[6:7], vcc
	s_cbranch_execz .LBB0_1604
	s_waitcnt lgkmcnt(0)
	v_pk_add_f32 v[0:1], v[90:91], v[92:93]
	ds_write_b64 v217, v[0:1] offset:512
.LBB0_1604:
	s_or_b64 exec, exec, s[6:7]
	v_add_u32_e32 v0, 0x90, v180
	v_ashrrev_i32_e32 v1, 31, v0
	v_lshlrev_b64 v[90:91], 11, v[0:1]
	v_lshl_add_u64 v[0:1], s[10:11], 0, v[90:91]
	v_lshl_add_u64 v[0:1], v[142:143], 1, v[0:1]
	s_waitcnt lgkmcnt(0)
	s_nop 0
	v_mul_f32_e32 v0, 0xbfb8aa3b, v86
	v_mul_f32_e32 v1, 0xbfb8aa3b, v87
	v_mul_f32_e32 v86, 0xbfb8aa3b, v88
	v_mul_f32_e32 v87, 0xbfb8aa3b, v89
	v_exp_f32_e32 v0, v0
	v_exp_f32_e32 v1, v1
	v_mul_f32_e32 v82, 0xbfb8aa3b, v82
	v_mul_f32_e32 v83, 0xbfb8aa3b, v83
	v_exp_f32_e32 v86, v86
	v_exp_f32_e32 v87, v87
	v_exp_f32_e32 v82, v82
	v_exp_f32_e32 v83, v83
	v_mul_f32_e32 v84, 0xbfb8aa3b, v84
	v_mul_f32_e32 v85, 0xbfb8aa3b, v85
	v_exp_f32_e32 v84, v84
	v_exp_f32_e32 v85, v85
	v_add_f32_e32 v0, 1.0, v0
	v_add_f32_e32 v1, 1.0, v1
	v_add_f32_e32 v86, 1.0, v86
	v_add_f32_e32 v87, 1.0, v87
	v_rcp_f32_e32 v0, v0
	v_rcp_f32_e32 v1, v1
	v_add_f32_e32 v88, 1.0, v82
	v_add_f32_e32 v89, 1.0, v83
	v_rcp_f32_e32 v82, v86
	v_rcp_f32_e32 v83, v87
	v_add_f32_e32 v96, 1.0, v84
	v_add_f32_e32 v97, 1.0, v85
	v_rcp_f32_e32 v84, v88
	v_rcp_f32_e32 v85, v89
	v_rcp_f32_e32 v86, v96
	v_rcp_f32_e32 v87, v97
	s_waitcnt vmcnt(2)
	v_lshlrev_b32_e32 v88, 16, v242
	v_and_b32_e32 v89, 0xffff0000, v242
	v_lshlrev_b32_e32 v92, 16, v243
	v_and_b32_e32 v93, 0xffff0000, v243
	v_pk_mul_f32 v[158:159], v[0:1], v[88:89]
	v_pk_mul_f32 v[156:157], v[82:83], v[92:93]
	v_add_f32_e32 v83, 0, v158
	v_mul_f32_e32 v82, v158, v158
	v_add_f32_e32 v83, v159, v83
	v_lshlrev_b32_e32 v96, 16, v244
	v_and_b32_e32 v97, 0xffff0000, v244
	v_lshlrev_b32_e32 v94, 16, v245
	v_and_b32_e32 v95, 0xffff0000, v245
	v_mov_b32_e32 v0, v156
	v_mov_b32_e32 v1, v158
	v_fmac_f32_e32 v82, v159, v159
	v_add_f32_e32 v83, v156, v83
	v_pk_mul_f32 v[154:155], v[84:85], v[96:97]
	v_pk_mul_f32 v[150:151], v[86:87], v[94:95]
	v_mul_f32_e32 v86, v157, v157
	v_pk_fma_f32 v[0:1], v[0:1], v[0:1], v[82:83] op_sel_hi:[1,1,0]
	v_mov_b32_e32 v84, v154
	v_mov_b32_e32 v85, v157
	v_pk_add_f32 v[0:1], v[86:87], v[0:1] op_sel_hi:[0,1]
	v_mul_f32_e32 v92, v155, v155
	v_add_f32_e32 v82, v157, v83
	v_pk_fma_f32 v[0:1], v[84:85], v[84:85], v[0:1]
	v_mov_b32_e32 v88, v150
	v_mov_b32_e32 v89, v155
	v_add_f32_e32 v82, v154, v82
	v_pk_add_f32 v[0:1], v[92:93], v[0:1] op_sel_hi:[0,1]
	v_pk_mul_f32 v[94:95], v[150:151], v[150:151]
	v_add_f32_e32 v82, v155, v82
	v_pk_fma_f32 v[0:1], v[88:89], v[88:89], v[0:1]
	v_add_f32_e32 v94, v150, v82
	v_pk_mov_b32 v[0:1], v[150:151], v[0:1] op_sel:[1,0]
	s_nop 0
	v_pk_add_f32 v[0:1], v[0:1], v[94:95]
	v_mov_b32_e32 v82, v0
	v_mov_b32_e32 v83, v1
	s_nop 1
	v_permlane16_swap_b32_e32 v82, v0
	v_permlane16_swap_b32_e32 v83, v1
	s_waitcnt lgkmcnt(0)
	v_pk_add_f32 v[82:83], v[0:1], v[82:83]
	v_mov_b32_e32 v84, v82
	v_mov_b32_e32 v85, v83
	s_nop 1
	v_permlane32_swap_b32_e32 v84, v82
	v_permlane32_swap_b32_e32 v85, v83
	s_and_saveexec_b64 s[6:7], vcc
	s_cbranch_execz .LBB0_1606
	s_waitcnt lgkmcnt(0)
	v_pk_add_f32 v[0:1], v[82:83], v[84:85]
	ds_write_b64 v217, v[0:1] offset:640
.LBB0_1606:
	s_or_b64 exec, exec, s[6:7]
	v_add_u32_e32 v0, 0xa0, v180
	v_ashrrev_i32_e32 v1, 31, v0
	v_lshlrev_b64 v[82:83], 11, v[0:1]
	v_lshl_add_u64 v[0:1], s[10:11], 0, v[82:83]
	v_lshl_add_u64 v[0:1], v[142:143], 1, v[0:1]
	s_waitcnt lgkmcnt(0)
	s_nop 0
	v_mul_f32_e32 v0, 0xbfb8aa3b, v78
	v_mul_f32_e32 v1, 0xbfb8aa3b, v79
	v_mul_f32_e32 v78, 0xbfb8aa3b, v80
	v_mul_f32_e32 v79, 0xbfb8aa3b, v81
	v_exp_f32_e32 v0, v0
	v_exp_f32_e32 v1, v1
	v_mul_f32_e32 v74, 0xbfb8aa3b, v74
	v_mul_f32_e32 v75, 0xbfb8aa3b, v75
	v_exp_f32_e32 v78, v78
	v_exp_f32_e32 v79, v79
	v_exp_f32_e32 v74, v74
	v_exp_f32_e32 v75, v75
	v_mul_f32_e32 v76, 0xbfb8aa3b, v76
	v_mul_f32_e32 v77, 0xbfb8aa3b, v77
	v_exp_f32_e32 v76, v76
	v_exp_f32_e32 v77, v77
	v_add_f32_e32 v0, 1.0, v0
	v_add_f32_e32 v1, 1.0, v1
	v_add_f32_e32 v78, 1.0, v78
	v_add_f32_e32 v79, 1.0, v79
	v_rcp_f32_e32 v0, v0
	v_rcp_f32_e32 v1, v1
	v_add_f32_e32 v80, 1.0, v74
	v_add_f32_e32 v81, 1.0, v75
	v_rcp_f32_e32 v74, v78
	v_rcp_f32_e32 v75, v79
	v_add_f32_e32 v88, 1.0, v76
	v_add_f32_e32 v89, 1.0, v77
	v_rcp_f32_e32 v76, v80
	v_rcp_f32_e32 v77, v81
	v_rcp_f32_e32 v78, v88
	v_rcp_f32_e32 v79, v89
	s_waitcnt vmcnt(1)
	v_lshlrev_b32_e32 v80, 16, v246
	v_and_b32_e32 v81, 0xffff0000, v246
	v_lshlrev_b32_e32 v84, 16, v247
	v_and_b32_e32 v85, 0xffff0000, v247
	v_pk_mul_f32 v[176:177], v[0:1], v[80:81]
	v_pk_mul_f32 v[172:173], v[74:75], v[84:85]
	v_add_f32_e32 v75, 0, v176
	v_mul_f32_e32 v74, v176, v176
	v_add_f32_e32 v75, v177, v75
	v_lshlrev_b32_e32 v88, 16, v248
	v_and_b32_e32 v89, 0xffff0000, v248
	v_lshlrev_b32_e32 v86, 16, v249
	v_and_b32_e32 v87, 0xffff0000, v249
	v_mov_b32_e32 v0, v172
	v_mov_b32_e32 v1, v176
	v_fmac_f32_e32 v74, v177, v177
	v_add_f32_e32 v75, v172, v75
	v_pk_mul_f32 v[170:171], v[76:77], v[88:89]
	v_pk_mul_f32 v[166:167], v[78:79], v[86:87]
	v_mul_f32_e32 v78, v173, v173
	v_pk_fma_f32 v[0:1], v[0:1], v[0:1], v[74:75] op_sel_hi:[1,1,0]
	v_mov_b32_e32 v76, v170
	v_mov_b32_e32 v77, v173
	v_pk_add_f32 v[0:1], v[78:79], v[0:1] op_sel_hi:[0,1]
	v_mul_f32_e32 v84, v171, v171
	v_add_f32_e32 v74, v173, v75
	v_pk_fma_f32 v[0:1], v[76:77], v[76:77], v[0:1]
	v_mov_b32_e32 v80, v166
	v_mov_b32_e32 v81, v171
	v_add_f32_e32 v74, v170, v74
	v_pk_add_f32 v[0:1], v[84:85], v[0:1] op_sel_hi:[0,1]
	v_pk_mul_f32 v[86:87], v[166:167], v[166:167]
	v_add_f32_e32 v74, v171, v74
	v_pk_fma_f32 v[0:1], v[80:81], v[80:81], v[0:1]
	v_add_f32_e32 v86, v166, v74
	v_pk_mov_b32 v[0:1], v[166:167], v[0:1] op_sel:[1,0]
	s_nop 0
	v_pk_add_f32 v[0:1], v[0:1], v[86:87]
	v_mov_b32_e32 v74, v0
	v_mov_b32_e32 v75, v1
	s_nop 1
	v_permlane16_swap_b32_e32 v74, v0
	v_permlane16_swap_b32_e32 v75, v1
	s_waitcnt lgkmcnt(0)
	v_pk_add_f32 v[74:75], v[0:1], v[74:75]
	v_mov_b32_e32 v76, v74
	v_mov_b32_e32 v77, v75
	s_nop 1
	v_permlane32_swap_b32_e32 v76, v74
	v_permlane32_swap_b32_e32 v77, v75
	s_and_saveexec_b64 s[6:7], vcc
	s_cbranch_execz .LBB0_1608
	s_waitcnt lgkmcnt(0)
	v_pk_add_f32 v[0:1], v[74:75], v[76:77]
	ds_write_b64 v217, v[0:1] offset:768
.LBB0_1608:
	s_or_b64 exec, exec, s[6:7]
	v_add_u32_e32 v0, 0xb0, v180
	v_ashrrev_i32_e32 v1, 31, v0
	v_lshlrev_b64 v[74:75], 11, v[0:1]
	v_lshl_add_u64 v[0:1], s[10:11], 0, v[74:75]
	v_lshl_add_u64 v[0:1], v[142:143], 1, v[0:1]
	s_waitcnt lgkmcnt(0)
	s_nop 0
	v_mul_f32_e32 v0, 0xbfb8aa3b, v70
	v_mul_f32_e32 v1, 0xbfb8aa3b, v71
	v_mul_f32_e32 v70, 0xbfb8aa3b, v72
	v_mul_f32_e32 v71, 0xbfb8aa3b, v73
	v_exp_f32_e32 v0, v0
	v_exp_f32_e32 v1, v1
	v_mul_f32_e32 v66, 0xbfb8aa3b, v66
	v_mul_f32_e32 v67, 0xbfb8aa3b, v67
	v_exp_f32_e32 v70, v70
	v_exp_f32_e32 v71, v71
	v_exp_f32_e32 v66, v66
	v_exp_f32_e32 v67, v67
	v_mul_f32_e32 v68, 0xbfb8aa3b, v68
	v_mul_f32_e32 v69, 0xbfb8aa3b, v69
	v_exp_f32_e32 v68, v68
	v_exp_f32_e32 v69, v69
	v_add_f32_e32 v0, 1.0, v0
	v_add_f32_e32 v1, 1.0, v1
	v_add_f32_e32 v70, 1.0, v70
	v_add_f32_e32 v71, 1.0, v71
	v_rcp_f32_e32 v0, v0
	v_rcp_f32_e32 v1, v1
	v_add_f32_e32 v72, 1.0, v66
	v_add_f32_e32 v73, 1.0, v67
	v_rcp_f32_e32 v66, v70
	v_rcp_f32_e32 v67, v71
	v_add_f32_e32 v80, 1.0, v68
	v_add_f32_e32 v81, 1.0, v69
	v_rcp_f32_e32 v68, v72
	v_rcp_f32_e32 v69, v73
	v_rcp_f32_e32 v70, v80
	v_rcp_f32_e32 v71, v81
	s_waitcnt vmcnt(0)
	v_lshlrev_b32_e32 v72, 16, v250
	v_and_b32_e32 v73, 0xffff0000, v250
	v_lshlrev_b32_e32 v76, 16, v251
	v_and_b32_e32 v77, 0xffff0000, v251
	v_pk_mul_f32 v[190:191], v[0:1], v[72:73]
	v_pk_mul_f32 v[188:189], v[66:67], v[76:77]
	v_add_f32_e32 v67, 0, v190
	v_mul_f32_e32 v66, v190, v190
	v_add_f32_e32 v67, v191, v67
	v_lshlrev_b32_e32 v80, 16, v252
	v_and_b32_e32 v81, 0xffff0000, v252
	v_lshlrev_b32_e32 v78, 16, v253
	v_and_b32_e32 v79, 0xffff0000, v253
	v_mov_b32_e32 v0, v188
	v_mov_b32_e32 v1, v190
	v_fmac_f32_e32 v66, v191, v191
	v_add_f32_e32 v67, v188, v67
	v_pk_mul_f32 v[184:185], v[68:69], v[80:81]
	v_pk_mul_f32 v[180:181], v[70:71], v[78:79]
	v_mul_f32_e32 v70, v189, v189
	v_pk_fma_f32 v[0:1], v[0:1], v[0:1], v[66:67] op_sel_hi:[1,1,0]
	v_mov_b32_e32 v68, v184
	v_mov_b32_e32 v69, v189
	v_pk_add_f32 v[0:1], v[70:71], v[0:1] op_sel_hi:[0,1]
	v_mul_f32_e32 v76, v185, v185
	v_add_f32_e32 v66, v189, v67
	v_pk_fma_f32 v[0:1], v[68:69], v[68:69], v[0:1]
	v_mov_b32_e32 v72, v180
	v_mov_b32_e32 v73, v185
	v_add_f32_e32 v66, v184, v66
	v_pk_add_f32 v[0:1], v[76:77], v[0:1] op_sel_hi:[0,1]
	v_pk_mul_f32 v[78:79], v[180:181], v[180:181]
	v_add_f32_e32 v66, v185, v66
	v_pk_fma_f32 v[0:1], v[72:73], v[72:73], v[0:1]
	v_add_f32_e32 v78, v180, v66
	v_pk_mov_b32 v[0:1], v[180:181], v[0:1] op_sel:[1,0]
	s_nop 0
	v_pk_add_f32 v[0:1], v[0:1], v[78:79]
	v_mov_b32_e32 v66, v0
	v_mov_b32_e32 v67, v1
	s_nop 1
	v_permlane16_swap_b32_e32 v66, v0
	v_permlane16_swap_b32_e32 v67, v1
	s_waitcnt lgkmcnt(0)
	v_pk_add_f32 v[66:67], v[0:1], v[66:67]
	v_mov_b32_e32 v68, v66
	v_mov_b32_e32 v69, v67
	s_nop 1
	v_permlane32_swap_b32_e32 v68, v66
	v_permlane32_swap_b32_e32 v69, v67
	s_and_saveexec_b64 s[6:7], vcc
	s_cbranch_execz .LBB0_1610
	s_waitcnt lgkmcnt(0)
	v_pk_add_f32 v[0:1], v[66:67], v[68:69]
	ds_write_b64 v217, v[0:1] offset:896
